# gate/up: epilogue no longer re-aligns the two wave halves (stagger kept across units; one alignment barrier only after the last unit)
# baseline (speedup 1.0000x reference)
; #define PG8_BAR __builtin_amdgcn_s_barrier()
; template <class Desc, class Epi, bool ALIGN_EPI>
; __device__ __forceinline__ void gemm_phase(LAS unsigned char* lds, const Desc& D, const Epi& E, int G, int c) {
;     ...
;         if constexpr (ALIGN_EPI) { if (wr == 0) PG8_BAR; }
.LBB0_1591:
	s_andn2_b64 vcc, s[26:27], s[40:41]
	s_cbranch_vccz .LBB0_1593
	s_barrier

;     __device__ __forceinline__ int nt(const Unit& u) const { return (u.pn >> 1) < 2 ? 22 : 20; }
; #define PG8_BAR __builtin_amdgcn_s_barrier()
; template <class Desc, class Epi, bool ALIGN_EPI>
; __device__ __forceinline__ void gemm_phase(LAS unsigned char* lds, const Desc& D, const Epi& E, int G, int c) {
;     ...
;         cur = nxt; cA = nA; cB = nB; ++ui; nt = D.nt(cur);
;         if constexpr (ALIGN_EPI) { if (wr == 1) PG8_BAR; }
.LBB0_1598:
	s_cmp_lt_i32 s70, 0
	s_cselect_b32 s2, 64, 32
	s_andn2_b64 vcc, exec, s[10:11]
	s_cbranch_vccnz .LBB0_1569
	s_branch .LBB0_1569
